# combo16: combo11 + accumulator zero-init between tiles uses one idle-pipe MFMA (0*0+0) per 16-register group instead of VALU moves
# baseline (speedup 1.0000x reference)
; template <class Epi, class Sched, bool ALIGN_EPI = false, bool SP2 = false>
; __device__ __forceinline__ void gemm_phase(PG8_LAS unsigned char* lds, const Gemm g, const Sched& S, const Epi& E, const int tid_arg) {
;     ...
;         const bool has_next = S.next(ui + 1, nxt);
;         const char* nA = has_next ? (const char*)g.A + (size_t)nxt.pm * tstep : cA; const char* nB = has_next ? (const char*)g.Bt + (size_t)nxt.pn * tstep : cB;
;     ...
; #pragma unroll
;         for (int a = 0; a < 2; ++a)
; #pragma unroll
;             for (int b = 0; b < 2; ++b)
; #pragma unroll
;                 for (int m = 0; m < 4; ++m)
; #pragma unroll
;                     for (int n = 0; n < 2; ++n) acc[a][b][m][n] = (f32x4){0.f, 0.f, 0.f, 0.f};
;         cur = nxt; cA = nA; cB = nB; ++ui;
.LBB0_252:
	s_ashr_i32 s23, s22, 31
	s_lshl_b64 s[0:1], s[22:23], 19
	s_add_u32 s24, s2, s0
	s_addc_u32 s25, s3, s1
	s_and_b64 s[0:1], s[4:5], exec
	s_cselect_b32 s23, s25, s35
	s_cselect_b32 s36, s24, s34
	s_ashr_i32 s21, s20, 31
	s_lshl_b64 s[0:1], s[20:21], 19
	s_add_u32 s26, s33, s0
	s_addc_u32 s27, s38, s1
	s_and_b64 s[0:1], s[4:5], exec
	s_cselect_b32 s21, s27, s9
	s_cselect_b32 s37, s26, s8
	s_add_u32 s68, s8, 0x100
	s_addc_u32 s69, s9, 0
	s_add_u32 s8, s34, 0x40080
	v_mov_b32_e32 v0, 0
	s_addc_u32 s9, s35, 0
	s_mov_b32 s70, -2
	v_mov_b32_e32 v1, v0
	v_mov_b64_e32 v[2:3], 0
	v_mov_b64_e32 v[4:5], 0
	v_mov_b64_e32 v[6:7], 0
	v_mov_b64_e32 v[8:9], 0
	v_mov_b64_e32 v[10:11], 0
	v_mov_b64_e32 v[12:13], 0
	v_mov_b64_e32 v[14:15], 0
	v_mov_b64_e32 v[16:17], 0
	v_mov_b64_e32 v[114:115], 0
	v_mov_b64_e32 v[116:117], 0
	v_mov_b64_e32 v[118:119], 0
	v_mov_b64_e32 v[120:121], 0
	v_mov_b64_e32 v[122:123], 0
	v_mov_b64_e32 v[124:125], 0
	v_mov_b64_e32 v[126:127], 0
	s_nop 1
	v_mfma_f32_32x32x16_bf16 v[18:33], v[2:5], v[2:5], 0
	v_mfma_f32_32x32x16_bf16 v[34:49], v[2:5], v[2:5], 0
	v_mfma_f32_32x32x16_bf16 v[50:65], v[2:5], v[2:5], 0
	v_mfma_f32_32x32x16_bf16 v[66:81], v[2:5], v[2:5], 0
	v_mfma_f32_32x32x16_bf16 v[82:97], v[2:5], v[2:5], 0
	v_mfma_f32_32x32x16_bf16 v[98:113], v[2:5], v[2:5], 0

; template <class Epi, class Sched, bool ALIGN_EPI = false, bool SP2 = false>
; __device__ __forceinline__ void gemm_phase(PG8_LAS unsigned char* lds, const Gemm g, const Sched& S, const Epi& E, const int tid_arg) {
;     ...
;         const bool has_next = S.next(ui + 1, nxt);
;         const char* nA = has_next ? (const char*)g.A + (size_t)nxt.pm * tstep : cA; const char* nB = has_next ? (const char*)g.Bt + (size_t)nxt.pn * tstep : cB;
;     ...
; #pragma unroll
;         for (int a = 0; a < 2; ++a)
; #pragma unroll
;             for (int b = 0; b < 2; ++b)
; #pragma unroll
;                 for (int m = 0; m < 4; ++m)
; #pragma unroll
;                     for (int n = 0; n < 2; ++n) acc[a][b][m][n] = (f32x4){0.f, 0.f, 0.f, 0.f};
;         cur = nxt; cA = nA; cB = nB; ++ui;
.LBB0_684:
	s_ashr_i32 s37, s36, 31
	s_lshl_b64 s[0:1], s[36:37], 19
	s_add_u32 s38, s2, s0
	s_addc_u32 s39, s3, s1
	s_and_b64 s[0:1], s[12:13], exec
	s_cselect_b32 s17, s39, s5
	s_cselect_b32 s37, s38, s4
	s_ashr_i32 s35, s34, 31
	s_lshl_b64 s[0:1], s[34:35], 19
	s_add_u32 s40, s33, s0
	s_addc_u32 s41, s48, s1
	s_and_b64 s[0:1], s[12:13], exec
	s_cselect_b32 s35, s41, s11
	s_cselect_b32 s46, s40, s10
	s_add_u32 s47, s10, 0x100
	v_mov_b32_e32 v0, 0
	s_addc_u32 s78, s11, 0
	s_mov_b32 s79, -2
	v_mov_b32_e32 v1, v0
	v_mov_b32_e32 v2, v0
	v_mov_b32_e32 v3, v0
	v_mov_b32_e32 v64, v0
	v_mov_b32_e32 v65, v0
	v_mov_b32_e32 v66, v0
	v_mov_b32_e32 v67, v0
	v_mov_b32_e32 v8, v0
	v_mov_b32_e32 v9, v0
	v_mov_b32_e32 v10, v0
	v_mov_b32_e32 v11, v0
	v_mov_b32_e32 v76, v0
	v_mov_b32_e32 v77, v0
	v_mov_b32_e32 v78, v0
	v_mov_b32_e32 v79, v0
	v_mov_b32_e32 v16, v0
	v_mov_b32_e32 v17, v0
	v_mov_b32_e32 v18, v0
	v_mov_b32_e32 v19, v0
	s_waitcnt vmcnt(0)
	v_mov_b64_e32 v[4:5], 0
	v_mov_b64_e32 v[6:7], 0
	v_mov_b64_e32 v[12:13], 0
	v_mov_b64_e32 v[14:15], 0
	v_mov_b64_e32 v[20:21], 0
	v_mov_b64_e32 v[22:23], 0
	v_mov_b64_e32 v[24:25], 0
	v_mov_b64_e32 v[26:27], 0
	v_mov_b64_e32 v[28:29], 0
	v_mov_b64_e32 v[30:31], 0
	v_mov_b64_e32 v[32:33], 0
	v_mov_b64_e32 v[34:35], 0
	v_mov_b64_e32 v[52:53], 0
	v_mov_b64_e32 v[54:55], 0
	v_mov_b64_e32 v[56:57], 0
	v_mov_b64_e32 v[58:59], 0
	v_mov_b64_e32 v[60:61], 0
	v_mov_b64_e32 v[62:63], 0
	v_mov_b64_e32 v[68:69], 0
	v_mov_b64_e32 v[70:71], 0
	v_mov_b64_e32 v[96:97], 0
	v_mov_b64_e32 v[98:99], 0
	s_nop 1
	v_mfma_f32_32x32x16_bf16 v[36:51], v[20:23], v[20:23], 0
	v_mfma_f32_32x32x16_bf16 v[80:95], v[20:23], v[20:23], 0
	v_mfma_f32_32x32x16_bf16 v[104:119], v[20:23], v[20:23], 0
	v_mfma_f32_32x32x16_bf16 v[120:135], v[20:23], v[20:23], 0

; template <class Epi, class Sched, bool ALIGN_EPI = false, bool SP2 = false>
; __device__ __forceinline__ void gemm_phase(PG8_LAS unsigned char* lds, const Gemm g, const Sched& S, const Epi& E, const int tid_arg) {
;     ...
; #pragma unroll
;         for (int a = 0; a < 2; ++a)
; #pragma unroll
;             for (int b = 0; b < 2; ++b)
; #pragma unroll
;                 for (int m = 0; m < 4; ++m)
; #pragma unroll
;                     for (int n = 0; n < 2; ++n) acc[a][b][m][n] = (f32x4){0.f, 0.f, 0.f, 0.f};
;         cur = nxt; cA = nA; cB = nB; ++ui;
.LBB0_870:
	s_add_u32 s55, s22, 0x100
	v_mov_b32_e32 v0, 0
	s_addc_u32 s56, s23, 0
	s_mov_b32 s57, -2
	v_mov_b32_e32 v1, v0
	v_mov_b64_e32 v[2:3], 0
	v_mov_b64_e32 v[4:5], 0
	v_mov_b64_e32 v[6:7], 0
	v_mov_b64_e32 v[8:9], 0
	v_mov_b64_e32 v[10:11], 0
	v_mov_b64_e32 v[12:13], 0
	v_mov_b64_e32 v[14:15], 0
	v_mov_b64_e32 v[16:17], 0
	v_mov_b64_e32 v[114:115], 0
	v_mov_b64_e32 v[116:117], 0
	v_mov_b64_e32 v[118:119], 0
	v_mov_b64_e32 v[120:121], 0
	v_mov_b64_e32 v[122:123], 0
	v_mov_b64_e32 v[124:125], 0
	v_mov_b64_e32 v[126:127], 0
	s_nop 1
	v_mfma_f32_32x32x16_bf16 v[18:33], v[2:5], v[2:5], 0
	v_mfma_f32_32x32x16_bf16 v[34:49], v[2:5], v[2:5], 0
	v_mfma_f32_32x32x16_bf16 v[50:65], v[2:5], v[2:5], 0
	v_mfma_f32_32x32x16_bf16 v[66:81], v[2:5], v[2:5], 0
	v_mfma_f32_32x32x16_bf16 v[82:97], v[2:5], v[2:5], 0
	v_mfma_f32_32x32x16_bf16 v[98:113], v[2:5], v[2:5], 0

; template <class Epi, class Sched, bool ALIGN_EPI = false, bool SP2 = false>
; __device__ __forceinline__ void gemm_phase(PG8_LAS unsigned char* lds, const Gemm g, const Sched& S, const Epi& E, const int tid_arg) {
;     ...
;         const bool has_next = S.next(ui + 1, nxt);
;         const char* nA = has_next ? (const char*)g.A + (size_t)nxt.pm * tstep : cA; const char* nB = has_next ? (const char*)g.Bt + (size_t)nxt.pn * tstep : cB;
;     ...
; #pragma unroll
;         for (int a = 0; a < 2; ++a)
; #pragma unroll
;             for (int b = 0; b < 2; ++b)
; #pragma unroll
;                 for (int m = 0; m < 4; ++m)
; #pragma unroll
;                     for (int n = 0; n < 2; ++n) acc[a][b][m][n] = (f32x4){0.f, 0.f, 0.f, 0.f};
;         cur = nxt; cA = nA; cB = nB; ++ui;
.LBB0_964:
	s_ashr_i32 s35, s34, 31
	s_lshl_b64 s[0:1], s[34:35], 19
	s_add_u32 s36, s3, s0
	s_addc_u32 s37, s33, s1
	s_and_b64 s[0:1], s[10:11], exec
	s_cselect_b32 s35, s37, s43
	s_cselect_b32 s68, s36, s42
	s_ashr_i32 s31, s30, 31
	s_lshl_b64 s[0:1], s[30:31], 19
	s_add_u32 s38, s44, s0
	s_addc_u32 s39, s45, s1
	s_and_b64 s[0:1], s[10:11], exec
	s_cselect_b32 s31, s39, s41
	s_cselect_b32 s69, s38, s40
	s_add_u32 s70, s40, 0x100
	s_addc_u32 s71, s41, 0
	s_add_u32 s40, s42, 0x40080
	v_mov_b32_e32 v0, 0
	s_addc_u32 s41, s43, 0
	s_mov_b32 s72, -2
	v_mov_b32_e32 v1, v0
	v_mov_b64_e32 v[2:3], 0
	v_mov_b64_e32 v[4:5], 0
	v_mov_b64_e32 v[6:7], 0
	v_mov_b64_e32 v[8:9], 0
	v_mov_b64_e32 v[10:11], 0
	v_mov_b64_e32 v[12:13], 0
	v_mov_b64_e32 v[14:15], 0
	v_mov_b64_e32 v[16:17], 0
	v_mov_b64_e32 v[114:115], 0
	v_mov_b64_e32 v[116:117], 0
	v_mov_b64_e32 v[118:119], 0
	v_mov_b64_e32 v[120:121], 0
	v_mov_b64_e32 v[122:123], 0
	v_mov_b64_e32 v[124:125], 0
	v_mov_b64_e32 v[126:127], 0
	s_nop 1
	v_mfma_f32_32x32x16_bf16 v[18:33], v[2:5], v[2:5], 0
	v_mfma_f32_32x32x16_bf16 v[34:49], v[2:5], v[2:5], 0
	v_mfma_f32_32x32x16_bf16 v[50:65], v[2:5], v[2:5], 0
	v_mfma_f32_32x32x16_bf16 v[66:81], v[2:5], v[2:5], 0
	v_mfma_f32_32x32x16_bf16 v[82:97], v[2:5], v[2:5], 0
	v_mfma_f32_32x32x16_bf16 v[98:113], v[2:5], v[2:5], 0

; template <class Epi, class Sched, bool ALIGN_EPI = false, bool SP2 = false>
; __device__ __forceinline__ void gemm_phase(PG8_LAS unsigned char* lds, const Gemm g, const Sched& S, const Epi& E, const int tid_arg) {
;     ...
;     Unit cur, nxt; int ui = 0;
;     if (!S.next(0, cur)) return;
;     f32x4 acc[2][2][4][2];
; #pragma unroll
;     for (int a = 0; a < 2; ++a)
; #pragma unroll
;         for (int b = 0; b < 2; ++b)
; #pragma unroll
;             for (int m = 0; m < 4; ++m)
; #pragma unroll
;                 for (int n = 0; n < 2; ++n) acc[a][b][m][n] = (f32x4){0.f, 0.f, 0.f, 0.f};
;     bf16x8 At[4][2], B0[2][2], B1[2][2];
;     const char* cA = (const char*)g.A + (size_t)cur.pm * tstep; const char* cB = (const char*)g.Bt + (size_t)cur.pn * tstep;
;     ...
; #pragma unroll
;         for (int a = 0; a < 2; ++a)
; #pragma unroll
;             for (int b = 0; b < 2; ++b)
; #pragma unroll
;                 for (int m = 0; m < 4; ++m)
; #pragma unroll
;                     for (int n = 0; n < 2; ++n) acc[a][b][m][n] = (f32x4){0.f, 0.f, 0.f, 0.f};
;         cur = nxt; cA = nA; cB = nB; ++ui;
.LBB0_1044:
	v_mov_b32_e32 v127, 0
	s_and_b64 vcc, exec, s[10:11]
	v_mov_b32_e32 v126, v127
	v_mov_b64_e32 v[0:1], 0
	v_mov_b64_e32 v[2:3], 0
	v_mov_b64_e32 v[4:5], 0
	v_mov_b64_e32 v[6:7], 0
	v_mov_b64_e32 v[8:9], 0
	v_mov_b64_e32 v[10:11], 0
	v_mov_b64_e32 v[12:13], 0
	v_mov_b64_e32 v[14:15], 0
	v_mov_b64_e32 v[112:113], 0
	v_mov_b64_e32 v[114:115], 0
	v_mov_b64_e32 v[116:117], 0
	v_mov_b64_e32 v[118:119], 0
	v_mov_b64_e32 v[120:121], 0
	v_mov_b64_e32 v[122:123], 0
	v_mov_b64_e32 v[124:125], 0
	s_nop 1
	v_mfma_f32_32x32x16_bf16 v[16:31], v[0:3], v[0:3], 0
	v_mfma_f32_32x32x16_bf16 v[32:47], v[0:3], v[0:3], 0
	v_mfma_f32_32x32x16_bf16 v[48:63], v[0:3], v[0:3], 0
	v_mfma_f32_32x32x16_bf16 v[64:79], v[0:3], v[0:3], 0
	v_mfma_f32_32x32x16_bf16 v[80:95], v[0:3], v[0:3], 0
	v_mfma_f32_32x32x16_bf16 v[96:111], v[0:3], v[0:3], 0
	s_cbranch_vccnz .LBB0_1047
	s_add_u32 s60, s4, 0x100
	s_addc_u32 s61, s5, 0
	s_add_u32 s4, s30, 0x80
	v_mov_b32_e32 v0, 0
	s_addc_u32 s5, s31, 0
	s_mov_b32 s0, 0
	v_mov_b32_e32 v1, v0
	v_mov_b64_e32 v[2:3], 0
	v_mov_b64_e32 v[4:5], 0
	v_mov_b64_e32 v[6:7], 0
	v_mov_b64_e32 v[8:9], 0
	v_mov_b64_e32 v[10:11], 0
	v_mov_b64_e32 v[12:13], 0
	v_mov_b64_e32 v[14:15], 0
	v_mov_b64_e32 v[16:17], 0
	v_mov_b64_e32 v[114:115], 0
	v_mov_b64_e32 v[116:117], 0
	v_mov_b64_e32 v[118:119], 0
	v_mov_b64_e32 v[120:121], 0
	v_mov_b64_e32 v[122:123], 0
	v_mov_b64_e32 v[124:125], 0
	v_mov_b64_e32 v[126:127], 0
	s_nop 1
	v_mfma_f32_32x32x16_bf16 v[18:33], v[2:5], v[2:5], 0
	v_mfma_f32_32x32x16_bf16 v[34:49], v[2:5], v[2:5], 0
	v_mfma_f32_32x32x16_bf16 v[50:65], v[2:5], v[2:5], 0
	v_mfma_f32_32x32x16_bf16 v[66:81], v[2:5], v[2:5], 0
	v_mfma_f32_32x32x16_bf16 v[82:97], v[2:5], v[2:5], 0
	v_mfma_f32_32x32x16_bf16 v[98:113], v[2:5], v[2:5], 0

; template <class Epi, class Sched, bool ALIGN_EPI = false, bool SP2 = false>
; __device__ __forceinline__ void gemm_phase(PG8_LAS unsigned char* lds, const Gemm g, const Sched& S, const Epi& E, const int tid_arg) {
;     ...
;         const bool has_next = S.next(ui + 1, nxt);
;         const char* nA = has_next ? (const char*)g.A + (size_t)nxt.pm * tstep : cA; const char* nB = has_next ? (const char*)g.Bt + (size_t)nxt.pn * tstep : cB;
;     ...
; #pragma unroll
;         for (int a = 0; a < 2; ++a)
; #pragma unroll
;             for (int b = 0; b < 2; ++b)
; #pragma unroll
;                 for (int m = 0; m < 4; ++m)
; #pragma unroll
;                     for (int n = 0; n < 2; ++n) acc[a][b][m][n] = (f32x4){0.f, 0.f, 0.f, 0.f};
;         cur = nxt; cA = nA; cB = nB; ++ui;
.LBB0_1178:
	s_ashr_i32 s25, s24, 31
	s_lshl_b64 s[0:1], s[24:25], 19
	s_add_u32 s26, s2, s0
	s_addc_u32 s27, s3, s1
	s_and_b64 s[0:1], s[6:7], exec
	s_cselect_b32 s25, s27, s11
	s_cselect_b32 s36, s26, s10
	s_ashr_i32 s23, s22, 31
	s_lshl_b64 s[0:1], s[22:23], 19
	s_add_u32 s28, s33, s0
	s_addc_u32 s29, s38, s1
	s_and_b64 s[0:1], s[6:7], exec
	s_cselect_b32 s23, s29, s5
	s_cselect_b32 s37, s28, s4
	s_add_u32 s66, s4, 0x100
	s_addc_u32 s67, s5, 0
	s_add_u32 s4, s10, 0x40080
	v_mov_b32_e32 v0, 0
	s_addc_u32 s5, s11, 0
	s_mov_b32 s68, -2
	v_mov_b32_e32 v1, v0
	v_mov_b32_e32 v2, v0
	v_mov_b32_e32 v3, v0
	v_mov_b32_e32 v4, v0
	v_mov_b32_e32 v5, v0
	v_mov_b32_e32 v6, v0
	v_mov_b32_e32 v7, v0
	s_waitcnt vmcnt(0)
	v_mov_b64_e32 v[8:9], 0
	v_mov_b64_e32 v[10:11], 0
	v_mov_b64_e32 v[12:13], 0
	v_mov_b64_e32 v[14:15], 0
	v_mov_b64_e32 v[16:17], 0
	v_mov_b64_e32 v[18:19], 0
	v_mov_b64_e32 v[20:21], 0
	v_mov_b64_e32 v[22:23], 0
	v_mov_b64_e32 v[120:121], 0
	v_mov_b64_e32 v[122:123], 0
	v_mov_b64_e32 v[124:125], 0
	v_mov_b64_e32 v[126:127], 0
	s_nop 1
	v_mfma_f32_32x32x16_bf16 v[24:39], v[8:11], v[8:11], 0
	v_mfma_f32_32x32x16_bf16 v[40:55], v[8:11], v[8:11], 0
	v_mfma_f32_32x32x16_bf16 v[56:71], v[8:11], v[8:11], 0
	v_mfma_f32_32x32x16_bf16 v[72:87], v[8:11], v[8:11], 0
	v_mfma_f32_32x32x16_bf16 v[88:103], v[8:11], v[8:11], 0
	v_mfma_f32_32x32x16_bf16 v[104:119], v[8:11], v[8:11], 0

; template <class Epi, class Sched, bool ALIGN_EPI = false, bool SP2 = false>
; __device__ __forceinline__ void gemm_phase(PG8_LAS unsigned char* lds, const Gemm g, const Sched& S, const Epi& E, const int tid_arg) {
;     ...
;         const bool has_next = S.next(ui + 1, nxt);
;         const char* nA = has_next ? (const char*)g.A + (size_t)nxt.pm * tstep : cA; const char* nB = has_next ? (const char*)g.Bt + (size_t)nxt.pn * tstep : cB;
;     ...
; #pragma unroll
;         for (int a = 0; a < 2; ++a)
; #pragma unroll
;             for (int b = 0; b < 2; ++b)
; #pragma unroll
;                 for (int m = 0; m < 4; ++m)
; #pragma unroll
;                     for (int n = 0; n < 2; ++n) acc[a][b][m][n] = (f32x4){0.f, 0.f, 0.f, 0.f};
;         cur = nxt; cA = nA; cB = nB; ++ui;
.LBB0_1546:
	s_ashr_i32 s31, s30, 31
	s_lshl_b64 s[0:1], s[30:31], 19
	s_add_u32 s34, s2, s0
	s_addc_u32 s35, s3, s1
	s_and_b64 s[0:1], s[8:9], exec
	s_cselect_b32 s13, s35, s5
	s_cselect_b32 s31, s34, s4
	s_ashr_i32 s29, s28, 31
	s_lshl_b64 s[0:1], s[28:29], 19
	s_add_u32 s36, s44, s0
	s_addc_u32 s37, s45, s1
	s_and_b64 s[0:1], s[8:9], exec
	s_cselect_b32 s29, s37, s7
	s_cselect_b32 s42, s36, s6
	s_add_u32 s43, s6, 0x100
	v_mov_b32_e32 v0, 0
	s_addc_u32 s75, s7, 0
	s_mov_b32 s78, -2
	v_mov_b32_e32 v1, v0
	v_mov_b32_e32 v2, v0
	v_mov_b32_e32 v3, v0
	v_mov_b32_e32 v64, v0
	v_mov_b32_e32 v65, v0
	v_mov_b32_e32 v66, v0
	v_mov_b32_e32 v67, v0
	v_mov_b32_e32 v8, v0
	v_mov_b32_e32 v9, v0
	v_mov_b32_e32 v10, v0
	v_mov_b32_e32 v11, v0
	v_mov_b32_e32 v76, v0
	v_mov_b32_e32 v77, v0
	v_mov_b32_e32 v78, v0
	v_mov_b32_e32 v79, v0
	v_mov_b32_e32 v16, v0
	v_mov_b32_e32 v17, v0
	v_mov_b32_e32 v18, v0
	v_mov_b32_e32 v19, v0
	s_waitcnt vmcnt(0)
	v_mov_b64_e32 v[4:5], 0
	v_mov_b64_e32 v[6:7], 0
	v_mov_b64_e32 v[12:13], 0
	v_mov_b64_e32 v[14:15], 0
	v_mov_b64_e32 v[20:21], 0
	v_mov_b64_e32 v[22:23], 0
	v_mov_b64_e32 v[24:25], 0
	v_mov_b64_e32 v[26:27], 0
	v_mov_b64_e32 v[28:29], 0
	v_mov_b64_e32 v[30:31], 0
	v_mov_b64_e32 v[32:33], 0
	v_mov_b64_e32 v[34:35], 0
	v_mov_b64_e32 v[52:53], 0
	v_mov_b64_e32 v[54:55], 0
	v_mov_b64_e32 v[56:57], 0
	v_mov_b64_e32 v[58:59], 0
	v_mov_b64_e32 v[60:61], 0
	v_mov_b64_e32 v[62:63], 0
	v_mov_b64_e32 v[68:69], 0
	v_mov_b64_e32 v[70:71], 0
	v_mov_b64_e32 v[96:97], 0
	v_mov_b64_e32 v[98:99], 0
	s_nop 1
	v_mfma_f32_32x32x16_bf16 v[36:51], v[20:23], v[20:23], 0
	v_mfma_f32_32x32x16_bf16 v[80:95], v[20:23], v[20:23], 0
	v_mfma_f32_32x32x16_bf16 v[104:119], v[20:23], v[20:23], 0
	v_mfma_f32_32x32x16_bf16 v[120:135], v[20:23], v[20:23], 0

; template <class Epi, class Sched, bool ALIGN_EPI = false, bool SP2 = false>
; __device__ __forceinline__ void gemm_phase(PG8_LAS unsigned char* lds, const Gemm g, const Sched& S, const Epi& E, const int tid_arg) {
;     ...
;         const bool has_next = S.next(ui + 1, nxt);
;         const char* nA = has_next ? (const char*)g.A + (size_t)nxt.pm * tstep : cA; const char* nB = has_next ? (const char*)g.Bt + (size_t)nxt.pn * tstep : cB;
;     ...
; #pragma unroll
;         for (int a = 0; a < 2; ++a)
; #pragma unroll
;             for (int b = 0; b < 2; ++b)
; #pragma unroll
;                 for (int m = 0; m < 4; ++m)
; #pragma unroll
;                     for (int n = 0; n < 2; ++n) acc[a][b][m][n] = (f32x4){0.f, 0.f, 0.f, 0.f};
;         cur = nxt; cA = nA; cB = nB; ++ui;
.LBB0_1826:
	s_ashr_i32 s39, s38, 31
	s_lshl_b64 s[0:1], s[38:39], 19
	s_add_u32 s40, s3, s0
	s_addc_u32 s41, s33, s1
	s_and_b64 s[0:1], s[6:7], exec
	s_cselect_b32 s39, s41, s47
	s_cselect_b32 s75, s40, s46
	s_ashr_i32 s37, s36, 31
	s_lshl_b64 s[0:1], s[36:37], 19
	s_add_u32 s42, s48, s0
	s_addc_u32 s43, s49, s1
	s_and_b64 s[0:1], s[6:7], exec
	s_cselect_b32 s37, s43, s45
	s_cselect_b32 s78, s42, s44
	s_add_u32 s79, s44, 0x100
	s_addc_u32 s80, s45, 0
	s_add_u32 s44, s46, 0x40080
	v_mov_b32_e32 v0, 0
	s_addc_u32 s45, s47, 0
	s_mov_b32 s81, -2
	v_mov_b32_e32 v1, v0
	v_mov_b64_e32 v[2:3], 0
	v_mov_b64_e32 v[4:5], 0
	v_mov_b64_e32 v[6:7], 0
	v_mov_b64_e32 v[8:9], 0
	v_mov_b64_e32 v[10:11], 0
	v_mov_b64_e32 v[12:13], 0
	v_mov_b64_e32 v[14:15], 0
	v_mov_b64_e32 v[16:17], 0
	v_mov_b64_e32 v[114:115], 0
	v_mov_b64_e32 v[116:117], 0
	v_mov_b64_e32 v[118:119], 0
	v_mov_b64_e32 v[120:121], 0
	v_mov_b64_e32 v[122:123], 0
	v_mov_b64_e32 v[124:125], 0
	v_mov_b64_e32 v[126:127], 0
	s_nop 1
	v_mfma_f32_32x32x16_bf16 v[18:33], v[2:5], v[2:5], 0
	v_mfma_f32_32x32x16_bf16 v[34:49], v[2:5], v[2:5], 0
	v_mfma_f32_32x32x16_bf16 v[50:65], v[2:5], v[2:5], 0
	v_mfma_f32_32x32x16_bf16 v[66:81], v[2:5], v[2:5], 0
	v_mfma_f32_32x32x16_bf16 v[82:97], v[2:5], v[2:5], 0
	v_mfma_f32_32x32x16_bf16 v[98:113], v[2:5], v[2:5], 0

; template <class Epi, class Sched, bool ALIGN_EPI = false, bool SP2 = false>
; __device__ __forceinline__ void gemm_phase(PG8_LAS unsigned char* lds, const Gemm g, const Sched& S, const Epi& E, const int tid_arg) {
;     ...
;     Unit cur, nxt; int ui = 0;
;     if (!S.next(0, cur)) return;
;     f32x4 acc[2][2][4][2];
; #pragma unroll
;     for (int a = 0; a < 2; ++a)
; #pragma unroll
;         for (int b = 0; b < 2; ++b)
; #pragma unroll
;             for (int m = 0; m < 4; ++m)
; #pragma unroll
;                 for (int n = 0; n < 2; ++n) acc[a][b][m][n] = (f32x4){0.f, 0.f, 0.f, 0.f};
;     bf16x8 At[4][2], B0[2][2], B1[2][2];
;     const char* cA = (const char*)g.A + (size_t)cur.pm * tstep; const char* cB = (const char*)g.Bt + (size_t)cur.pn * tstep;
;     ...
; #pragma unroll
;         for (int a = 0; a < 2; ++a)
; #pragma unroll
;             for (int b = 0; b < 2; ++b)
; #pragma unroll
;                 for (int m = 0; m < 4; ++m)
; #pragma unroll
;                     for (int n = 0; n < 2; ++n) acc[a][b][m][n] = (f32x4){0.f, 0.f, 0.f, 0.f};
;         cur = nxt; cA = nA; cB = nB; ++ui;
.LBB0_1909:
	v_mov_b32_e32 v127, 0
	s_and_b64 vcc, exec, s[0:1]
	v_mov_b32_e32 v126, v127
	v_mov_b64_e32 v[0:1], 0
	v_mov_b64_e32 v[2:3], 0
	v_mov_b64_e32 v[4:5], 0
	v_mov_b64_e32 v[6:7], 0
	v_mov_b64_e32 v[8:9], 0
	v_mov_b64_e32 v[10:11], 0
	v_mov_b64_e32 v[12:13], 0
	v_mov_b64_e32 v[14:15], 0
	v_mov_b64_e32 v[112:113], 0
	v_mov_b64_e32 v[114:115], 0
	v_mov_b64_e32 v[116:117], 0
	v_mov_b64_e32 v[118:119], 0
	v_mov_b64_e32 v[120:121], 0
	v_mov_b64_e32 v[122:123], 0
	v_mov_b64_e32 v[124:125], 0
	s_nop 1
	v_mfma_f32_32x32x16_bf16 v[16:31], v[0:3], v[0:3], 0
	v_mfma_f32_32x32x16_bf16 v[32:47], v[0:3], v[0:3], 0
	v_mfma_f32_32x32x16_bf16 v[48:63], v[0:3], v[0:3], 0
	v_mfma_f32_32x32x16_bf16 v[64:79], v[0:3], v[0:3], 0
	v_mfma_f32_32x32x16_bf16 v[80:95], v[0:3], v[0:3], 0
	v_mfma_f32_32x32x16_bf16 v[96:111], v[0:3], v[0:3], 0
	s_cbranch_vccnz .LBB0_1912
	s_add_u32 s63, s34, 0x100
	s_addc_u32 s64, s35, 0
	s_add_u32 s6, s36, 0x80
	v_mov_b32_e32 v0, 0
	s_addc_u32 s7, s37, 0
	s_mov_b32 s34, 0
	v_mov_b32_e32 v1, v0
	v_mov_b64_e32 v[2:3], 0
	v_mov_b64_e32 v[4:5], 0
	v_mov_b64_e32 v[6:7], 0
	v_mov_b64_e32 v[8:9], 0
	v_mov_b64_e32 v[10:11], 0
	v_mov_b64_e32 v[12:13], 0
	v_mov_b64_e32 v[14:15], 0
	v_mov_b64_e32 v[16:17], 0
	v_mov_b64_e32 v[114:115], 0
	v_mov_b64_e32 v[116:117], 0
	v_mov_b64_e32 v[118:119], 0
	v_mov_b64_e32 v[120:121], 0
	v_mov_b64_e32 v[122:123], 0
	v_mov_b64_e32 v[124:125], 0
	v_mov_b64_e32 v[126:127], 0
	s_nop 1
	v_mfma_f32_32x32x16_bf16 v[18:33], v[2:5], v[2:5], 0
	v_mfma_f32_32x32x16_bf16 v[34:49], v[2:5], v[2:5], 0
	v_mfma_f32_32x32x16_bf16 v[50:65], v[2:5], v[2:5], 0
	v_mfma_f32_32x32x16_bf16 v[66:81], v[2:5], v[2:5], 0
	v_mfma_f32_32x32x16_bf16 v[82:97], v[2:5], v[2:5], 0
	v_mfma_f32_32x32x16_bf16 v[98:113], v[2:5], v[2:5], 0
